# stack42 + small per-workgroup stagger (0-1.8 us by (blockIdx>>3)&3) at the start of the attention phase
# baseline (speedup 1.0000x reference)
.LBB0_717:
	s_andn2_b64 vcc, exec, s[2:3]
	v_writelane_b32 v226, s40, 0
	v_and_b32_e32 v137, 63, v136
	s_nop 0
	v_writelane_b32 v226, s41, 1
	s_cbranch_vccnz .LBB0_894
	s_bfe_u32 s98, s10, 0x20003
	s_cmp_eq_u32 s98, 0
	s_cbranch_scc1 .Latt_stag_done
.Latt_stag:
	s_add_i32 s98, s98, -1
	s_cmp_eq_u32 s98, 0
	s_sleep 0x15
	s_cbranch_scc0 .Latt_stag
.Latt_stag_done:
	v_writelane_b32 v226, s4, 2
	s_waitcnt lgkmcnt(0)
	s_add_u32 s59, s28, 0xa400000
	s_addc_u32 s60, s29, 0
	v_writelane_b32 v226, s5, 3
	v_writelane_b32 v226, s94, 4
	s_load_dword s2, s[94:95], 0x10
	s_add_u32 s61, s28, 0x6400000
	s_addc_u32 s63, s29, 0
	v_add_u32_e32 v138, 64, v0
	v_cmp_lt_i32_e32 vcc, v139, v138
	s_waitcnt lgkmcnt(0)
	s_lshr_b32 s2, s2, 16
	s_cmp_lg_u32 s2, 0
	s_cselect_b64 s[2:3], -1, 0
	s_cmp_lg_u64 s[2:3], 0
	s_addc_u32 s64, s33, 0
	s_cmpk_eq_i32 s64, 0x100
	s_cselect_b64 s[12:13], -1, 0
	s_bfe_u32 s4, s96, 0x20006
	s_bfe_u32 s58, s96, 0x30006
	s_mul_i32 s2, s4, 0x2400
	s_add_i32 s66, s2, 0
	s_lshl_b32 s2, s58, 7
	s_lshl_b32 s3, s97, 2
	s_lshl_b32 s6, s97, 1
	s_bfe_u32 s5, s97, 0x10002
	s_and_b32 s3, s3, 16
	s_and_b32 s6, s6, 4
	s_add_i32 s70, s2, 0
	s_lshr_b32 s65, s10, 3
	s_add_i32 s66, s66, 0x18000
	s_lshl_b32 s67, s4, 5
	s_lshl_b32 s68, s58, 10
	s_or_b32 s69, s6, s3
	s_lshl_b32 s71, s5, 14
	s_add_i32 s70, s70, 0x21000
	s_cmp_lg_u32 0, -1
	s_cselect_b32 s2, 0, 0
	s_add_i32 s71, s71, s2
	s_lshl_b32 s2, s5, 13
	s_add_i32 s79, s2, 0
	s_xor_b32 s2, s5, 1
	s_lshl_b32 s3, s2, 7
	s_lshl_b32 s73, s5, 5
	s_lshl_b32 s6, s5, 7
	s_add_i32 s76, s66, s3
	s_lshl_b32 s3, s5, 11
	s_lshl_b32 s2, s2, 11
	s_add_i32 s72, s79, 0x10000
	s_or_b32 s74, s73, 31
	s_add_i32 s75, s66, s6
	s_add_i32 s77, s66, s3
	s_add_i32 s78, s66, s2
	s_cmp_lt_u32 s58, 4
	v_writelane_b32 v226, s95, 5
	s_cselect_b64 s[2:3], -1, 0
	s_mulk_i32 s5, 0xf880
	s_lshl_b32 s4, s4, 16
	v_cndmask_b32_e32 v0, v136, v139, vcc
	s_sub_i32 s81, s67, s73
	s_mov_b32 s9, 0
	v_writelane_b32 v226, s96, 6
	s_add_i32 s79, s79, 0x14000
	s_add_i32 s80, s77, s5
	v_lshlrev_b32_e32 v140, 2, v0
	s_addk_i32 s81, 0xff65
	s_sub_i32 s82, 0, s67
	s_or_b32 s11, s73, 0x9f
	s_lshl_b32 s84, s4, 1
	s_lshl_b32 s85, s6, 1
	v_mov_b32_e32 v129, 0
	s_movk_i32 s86, 0x4000
	s_movk_i32 s87, 0xbfff
	s_mov_b32 s88, 0x41000000
	v_mov_b32_e32 v141, 0xff800000
	s_mov_b32 s89, s10
	v_writelane_b32 v226, s97, 7
	s_branch .LBB0_720
